# combo19: combo18 + P5 epilogue rss loads issued together before the first row group
# speedup vs baseline: 1.0054x; 1.0050x over previous
; __device__ __forceinline__ unsigned cvt_pk_bf16(float lo, float hi) { unsigned r; asm volatile("v_cvt_pk_bf16_f32 %0, %1, %2" : "=v"(r) : "v"(lo), "v"(hi)); return r; }
;     __device__ __forceinline__ void operator()(const f32x4 (&acc)[2][2][4][2], const Unit& u, int wr, int wc, int fr, int fq) const {
;     ...
;             for (int m = 0; m < 4; ++m) { bf16_t* rowp = base + (size_t)(row0 + ai * HALF + m * 16) * ldc + col0;
;                 const float rs = rowss ? __builtin_amdgcn_rsqf(rowss[row0 + ai * HALF + m * 16] * (1.0f / 1024.0f) + 1e-6f) : 1.0f;
; #pragma unroll
;                 for (int bj = 0; bj < 2; ++bj) { f32x4 v0 = acc[ai][bj][m][0] * rs + bv[bj][0], v1 = acc[ai][bj][m][1] * rs + bv[bj][1];
;                     if (ACT == 1) { f32x2 a = gelu_pk((f32x2){v0[0], v0[1]}), b = gelu_pk((f32x2){v0[2], v0[3]}), c = gelu_pk((f32x2){v1[0], v1[1]}), d = gelu_pk((f32x2){v1[2], v1[3]});
;                         v0 = (f32x4){a.x, a.y, b.x, b.y}; v1 = (f32x4){c.x, c.y, d.x, d.y}; }
;                     if (ACT == 2) { v0 = __builtin_elementwise_max(v0, (f32x4){0.f, 0.f, 0.f, 0.f}); v1 = __builtin_elementwise_max(v1, (f32x4){0.f, 0.f, 0.f, 0.f}); v0 = v0 * v0; v1 = v1 * v1; }
;                     v0 = v0 * sc; v1 = v1 * sc; u32x4 w; w.x = cvt_pk_bf16(v0[0], v0[1]); w.y = cvt_pk_bf16(v0[2], v0[3]); w.z = cvt_pk_bf16(v1[0], v1[1]); w.w = cvt_pk_bf16(v1[2], v1[3]);
;                     *(u32x4*)(rowp + bj * HALF) = w; } }
.LBB0_1146:
	v_lshl_add_u32 v166, s33, 8, v168
	v_ashrrev_i32_e32 v167, 31, v166
	v_lshl_add_u64 v[156:157], v[166:167], 2, s[8:9]
	global_load_dword v172, v[156:157], off
	global_load_dword v174, v[156:157], off offset:64
	global_load_dword v176, v[156:157], off offset:128
	global_load_dword v178, v[156:157], off offset:192
	global_load_dword v180, v[156:157], off offset:512
	global_load_dword v182, v[156:157], off offset:576
	global_load_dword v184, v[156:157], off offset:640
	global_load_dword v186, v[156:157], off offset:704
	v_lshl_add_u64 v[158:159], v[154:155], 1, s[60:61]
	v_lshlrev_b64 v[154:155], 13, v[166:167]
	v_lshl_add_u64 v[154:155], v[158:159], 0, v[154:155]
	s_mov_b32 s4, 0x100000
	s_waitcnt vmcnt(0)
	v_fmamk_f32 v162, v172, 0x3a800000, v199
	v_rsq_f32_e32 v162, v162
	s_nop 0
	v_pk_fma_f32 v[142:143], v[142:143], v[162:163], v[66:67] op_sel_hi:[1,0,1]
	v_pk_fma_f32 v[140:141], v[140:141], v[162:163], v[64:65] op_sel_hi:[1,0,1]
	v_pk_fma_f32 v[138:139], v[138:139], v[162:163], v[58:59] op_sel_hi:[1,0,1]
	v_pk_fma_f32 v[136:137], v[136:137], v[162:163], v[56:57] op_sel_hi:[1,0,1]
	v_max_f32_e32 v141, 0, v141
	v_max_f32_e32 v140, 0, v140
	v_max_f32_e32 v143, 0, v143
	v_max_f32_e32 v142, 0, v142
	v_max_f32_e32 v137, 0, v137
	v_max_f32_e32 v136, 0, v136
	v_max_f32_e32 v139, 0, v139
	v_max_f32_e32 v138, 0, v138
	v_pk_fma_f32 v[132:133], v[132:133], v[162:163], v[68:69] op_sel_hi:[1,0,1]
	v_pk_fma_f32 v[130:131], v[130:131], v[162:163], v[62:63] op_sel_hi:[1,0,1]
	v_pk_fma_f32 v[128:129], v[128:129], v[162:163], v[60:61] op_sel_hi:[1,0,1]
	v_pk_mul_f32 v[142:143], v[142:143], v[142:143]
	v_pk_mul_f32 v[140:141], v[140:141], v[140:141]
	v_pk_mul_f32 v[164:165], v[138:139], v[138:139]
	v_pk_mul_f32 v[138:139], v[136:137], v[136:137]
	v_cvt_pk_bf16_f32 v136, v140, v141
	v_cvt_pk_bf16_f32 v137, v142, v143
	v_pk_fma_f32 v[134:135], v[134:135], v[162:163], v[70:71] op_sel_hi:[1,0,1]
	v_max_f32_e32 v133, 0, v133
	v_max_f32_e32 v132, 0, v132
	v_max_f32_e32 v129, 0, v129
	v_max_f32_e32 v128, 0, v128
	v_max_f32_e32 v131, 0, v131
	v_max_f32_e32 v130, 0, v130
	v_cvt_pk_bf16_f32 v138, v138, v139
	v_cvt_pk_bf16_f32 v139, v164, v165
	global_store_dwordx4 v[154:155], v[136:139], off
	v_max_f32_e32 v135, 0, v135
	v_max_f32_e32 v134, 0, v134
	v_pk_mul_f32 v[132:133], v[132:133], v[132:133]
	v_pk_mul_f32 v[136:137], v[130:131], v[130:131]
	v_pk_mul_f32 v[130:131], v[128:129], v[128:129]
	v_cvt_pk_bf16_f32 v128, v132, v133
	v_pk_mul_f32 v[134:135], v[134:135], v[134:135]
	s_nop 0
	v_cvt_pk_bf16_f32 v129, v134, v135
	v_cvt_pk_bf16_f32 v130, v130, v131
	v_cvt_pk_bf16_f32 v131, v136, v137
	global_store_dwordx4 v[154:155], v[128:131], off offset:256
	s_nop 1
	v_or_b32_e32 v128, 16, v166
	v_ashrrev_i32_e32 v129, 31, v128
	v_lshlrev_b64 v[130:131], 13, v[128:129]
	v_lshl_add_u64 v[130:131], v[158:159], 0, v[130:131]
	v_fmamk_f32 v128, v174, 0x3a800000, v199
	v_rsq_f32_e32 v128, v128
	s_nop 0
	v_pk_fma_f32 v[126:127], v[126:127], v[128:129], v[66:67] op_sel_hi:[1,0,1]
	v_pk_fma_f32 v[124:125], v[124:125], v[128:129], v[64:65] op_sel_hi:[1,0,1]
	v_pk_fma_f32 v[122:123], v[122:123], v[128:129], v[58:59] op_sel_hi:[1,0,1]
	v_pk_fma_f32 v[120:121], v[120:121], v[128:129], v[56:57] op_sel_hi:[1,0,1]
	v_max_f32_e32 v125, 0, v125
	v_max_f32_e32 v124, 0, v124
	v_max_f32_e32 v127, 0, v127
	v_max_f32_e32 v126, 0, v126
	v_max_f32_e32 v121, 0, v121
	v_max_f32_e32 v120, 0, v120
	v_max_f32_e32 v123, 0, v123
	v_max_f32_e32 v122, 0, v122
	v_pk_fma_f32 v[116:117], v[116:117], v[128:129], v[68:69] op_sel_hi:[1,0,1]
	v_pk_fma_f32 v[114:115], v[114:115], v[128:129], v[62:63] op_sel_hi:[1,0,1]
	v_pk_fma_f32 v[112:113], v[112:113], v[128:129], v[60:61] op_sel_hi:[1,0,1]
	v_pk_mul_f32 v[126:127], v[126:127], v[126:127]
	v_pk_mul_f32 v[124:125], v[124:125], v[124:125]
	v_pk_mul_f32 v[132:133], v[122:123], v[122:123]
	v_pk_mul_f32 v[122:123], v[120:121], v[120:121]
	v_cvt_pk_bf16_f32 v120, v124, v125
	v_cvt_pk_bf16_f32 v121, v126, v127
	v_pk_fma_f32 v[118:119], v[118:119], v[128:129], v[70:71] op_sel_hi:[1,0,1]
	v_max_f32_e32 v117, 0, v117
	v_max_f32_e32 v116, 0, v116
	v_max_f32_e32 v113, 0, v113
	v_max_f32_e32 v112, 0, v112
	v_max_f32_e32 v115, 0, v115
	v_max_f32_e32 v114, 0, v114
	v_cvt_pk_bf16_f32 v122, v122, v123
	v_cvt_pk_bf16_f32 v123, v132, v133
	global_store_dwordx4 v[130:131], v[120:123], off
	v_max_f32_e32 v119, 0, v119
	v_max_f32_e32 v118, 0, v118
	v_pk_mul_f32 v[116:117], v[116:117], v[116:117]
	v_pk_mul_f32 v[120:121], v[114:115], v[114:115]
	v_pk_mul_f32 v[114:115], v[112:113], v[112:113]
	v_cvt_pk_bf16_f32 v112, v116, v117
	v_pk_mul_f32 v[118:119], v[118:119], v[118:119]
	s_nop 0
	v_cvt_pk_bf16_f32 v113, v118, v119
	v_cvt_pk_bf16_f32 v114, v114, v115
	v_cvt_pk_bf16_f32 v115, v120, v121
	global_store_dwordx4 v[130:131], v[112:115], off offset:256
	s_nop 1
	v_or_b32_e32 v112, 32, v166
	v_ashrrev_i32_e32 v113, 31, v112
	v_lshlrev_b64 v[114:115], 13, v[112:113]
	v_lshl_add_u64 v[114:115], v[158:159], 0, v[114:115]
	v_fmamk_f32 v112, v176, 0x3a800000, v199
	v_rsq_f32_e32 v112, v112
	s_nop 0
	v_pk_fma_f32 v[110:111], v[110:111], v[112:113], v[66:67] op_sel_hi:[1,0,1]
	v_pk_fma_f32 v[108:109], v[108:109], v[112:113], v[64:65] op_sel_hi:[1,0,1]
	v_pk_fma_f32 v[106:107], v[106:107], v[112:113], v[58:59] op_sel_hi:[1,0,1]
	v_pk_fma_f32 v[104:105], v[104:105], v[112:113], v[56:57] op_sel_hi:[1,0,1]
	v_max_f32_e32 v109, 0, v109
	v_max_f32_e32 v108, 0, v108
	v_max_f32_e32 v111, 0, v111
	v_max_f32_e32 v110, 0, v110
	v_max_f32_e32 v105, 0, v105
	v_max_f32_e32 v104, 0, v104
	v_max_f32_e32 v107, 0, v107
	v_max_f32_e32 v106, 0, v106
	v_pk_fma_f32 v[98:99], v[98:99], v[112:113], v[62:63] op_sel_hi:[1,0,1]
; __device__ __forceinline__ unsigned cvt_pk_bf16(float lo, float hi) { unsigned r; asm volatile("v_cvt_pk_bf16_f32 %0, %1, %2" : "=v"(r) : "v"(lo), "v"(hi)); return r; }
;     __device__ __forceinline__ void operator()(const f32x4 (&acc)[2][2][4][2], const Unit& u, int wr, int wc, int fr, int fq) const {
;     ...
;             for (int m = 0; m < 4; ++m) { bf16_t* rowp = base + (size_t)(row0 + ai * HALF + m * 16) * ldc + col0;
;                 const float rs = rowss ? __builtin_amdgcn_rsqf(rowss[row0 + ai * HALF + m * 16] * (1.0f / 1024.0f) + 1e-6f) : 1.0f;
; #pragma unroll
;                 for (int bj = 0; bj < 2; ++bj) { f32x4 v0 = acc[ai][bj][m][0] * rs + bv[bj][0], v1 = acc[ai][bj][m][1] * rs + bv[bj][1];
;                     if (ACT == 1) { f32x2 a = gelu_pk((f32x2){v0[0], v0[1]}), b = gelu_pk((f32x2){v0[2], v0[3]}), c = gelu_pk((f32x2){v1[0], v1[1]}), d = gelu_pk((f32x2){v1[2], v1[3]});
;                         v0 = (f32x4){a.x, a.y, b.x, b.y}; v1 = (f32x4){c.x, c.y, d.x, d.y}; }
;                     if (ACT == 2) { v0 = __builtin_elementwise_max(v0, (f32x4){0.f, 0.f, 0.f, 0.f}); v1 = __builtin_elementwise_max(v1, (f32x4){0.f, 0.f, 0.f, 0.f}); v0 = v0 * v0; v1 = v1 * v1; }
;                     v0 = v0 * sc; v1 = v1 * sc; u32x4 w; w.x = cvt_pk_bf16(v0[0], v0[1]); w.y = cvt_pk_bf16(v0[2], v0[3]); w.z = cvt_pk_bf16(v1[0], v1[1]); w.w = cvt_pk_bf16(v1[2], v1[3]);
;                     *(u32x4*)(rowp + bj * HALF) = w; } }
	v_pk_fma_f32 v[96:97], v[96:97], v[112:113], v[60:61] op_sel_hi:[1,0,1]
	v_pk_mul_f32 v[110:111], v[110:111], v[110:111]
	v_pk_mul_f32 v[108:109], v[108:109], v[108:109]
	v_pk_mul_f32 v[116:117], v[106:107], v[106:107]
	v_pk_mul_f32 v[106:107], v[104:105], v[104:105]
	v_cvt_pk_bf16_f32 v104, v108, v109
	v_cvt_pk_bf16_f32 v105, v110, v111
	v_pk_fma_f32 v[102:103], v[102:103], v[112:113], v[70:71] op_sel_hi:[1,0,1]
	v_pk_fma_f32 v[100:101], v[100:101], v[112:113], v[68:69] op_sel_hi:[1,0,1]
	v_max_f32_e32 v97, 0, v97
	v_max_f32_e32 v96, 0, v96
	v_max_f32_e32 v99, 0, v99
	v_max_f32_e32 v98, 0, v98
	v_cvt_pk_bf16_f32 v106, v106, v107
	v_cvt_pk_bf16_f32 v107, v116, v117
	global_store_dwordx4 v[114:115], v[104:107], off
	v_max_f32_e32 v101, 0, v101
	v_max_f32_e32 v100, 0, v100
	v_max_f32_e32 v103, 0, v103
	v_max_f32_e32 v102, 0, v102
	v_pk_mul_f32 v[104:105], v[98:99], v[98:99]
	v_pk_mul_f32 v[98:99], v[96:97], v[96:97]
	v_pk_mul_f32 v[102:103], v[102:103], v[102:103]
	v_pk_mul_f32 v[100:101], v[100:101], v[100:101]
	s_nop 0
	v_cvt_pk_bf16_f32 v96, v100, v101
	v_cvt_pk_bf16_f32 v97, v102, v103
	v_cvt_pk_bf16_f32 v98, v98, v99
	v_cvt_pk_bf16_f32 v99, v104, v105
	global_store_dwordx4 v[114:115], v[96:99], off offset:256
	s_nop 1
	v_or_b32_e32 v98, 48, v166
	v_ashrrev_i32_e32 v99, 31, v98
	v_lshlrev_b64 v[96:97], 13, v[98:99]
	v_lshl_add_u64 v[96:97], v[158:159], 0, v[96:97]
	v_fmamk_f32 v98, v178, 0x3a800000, v199
	v_rsq_f32_e32 v98, v98
	s_nop 0
	v_pk_fma_f32 v[94:95], v[94:95], v[98:99], v[66:67] op_sel_hi:[1,0,1]
	v_pk_fma_f32 v[92:93], v[92:93], v[98:99], v[64:65] op_sel_hi:[1,0,1]
	v_pk_fma_f32 v[90:91], v[90:91], v[98:99], v[58:59] op_sel_hi:[1,0,1]
	v_pk_fma_f32 v[88:89], v[88:89], v[98:99], v[56:57] op_sel_hi:[1,0,1]
	v_max_f32_e32 v93, 0, v93
	v_max_f32_e32 v92, 0, v92
	v_max_f32_e32 v95, 0, v95
	v_max_f32_e32 v94, 0, v94
	v_max_f32_e32 v89, 0, v89
	v_max_f32_e32 v88, 0, v88
	v_max_f32_e32 v91, 0, v91
	v_max_f32_e32 v90, 0, v90
	v_pk_fma_f32 v[82:83], v[82:83], v[98:99], v[62:63] op_sel_hi:[1,0,1]
	v_pk_fma_f32 v[80:81], v[80:81], v[98:99], v[60:61] op_sel_hi:[1,0,1]
	v_pk_mul_f32 v[94:95], v[94:95], v[94:95]
	v_pk_mul_f32 v[92:93], v[92:93], v[92:93]
	v_pk_mul_f32 v[100:101], v[90:91], v[90:91]
	v_pk_mul_f32 v[90:91], v[88:89], v[88:89]
	v_cvt_pk_bf16_f32 v88, v92, v93
	v_cvt_pk_bf16_f32 v89, v94, v95
	v_pk_fma_f32 v[86:87], v[86:87], v[98:99], v[70:71] op_sel_hi:[1,0,1]
	v_pk_fma_f32 v[84:85], v[84:85], v[98:99], v[68:69] op_sel_hi:[1,0,1]
	v_max_f32_e32 v81, 0, v81
	v_max_f32_e32 v80, 0, v80
	v_max_f32_e32 v83, 0, v83
	v_max_f32_e32 v82, 0, v82
	v_cvt_pk_bf16_f32 v90, v90, v91
	v_cvt_pk_bf16_f32 v91, v100, v101
	global_store_dwordx4 v[96:97], v[88:91], off
	v_max_f32_e32 v85, 0, v85
	v_max_f32_e32 v84, 0, v84
	v_max_f32_e32 v87, 0, v87
	v_max_f32_e32 v86, 0, v86
	v_pk_mul_f32 v[88:89], v[82:83], v[82:83]
	v_pk_mul_f32 v[82:83], v[80:81], v[80:81]
	v_pk_mul_f32 v[86:87], v[86:87], v[86:87]
	v_pk_mul_f32 v[84:85], v[84:85], v[84:85]
	s_nop 0
	v_cvt_pk_bf16_f32 v80, v84, v85
	v_cvt_pk_bf16_f32 v81, v86, v87
	v_cvt_pk_bf16_f32 v82, v82, v83
	v_cvt_pk_bf16_f32 v83, v88, v89
	global_store_dwordx4 v[96:97], v[80:83], off offset:256
	s_nop 0
	s_nop 0
	v_lshl_add_u64 v[80:81], v[154:155], 0, s[70:71]
	v_fmamk_f32 v82, v180, 0x3a800000, v199
	v_rsq_f32_e32 v82, v82
	s_nop 0
	v_pk_fma_f32 v[76:77], v[76:77], v[82:83], v[64:65] op_sel_hi:[1,0,1]
	v_pk_fma_f32 v[74:75], v[74:75], v[82:83], v[58:59] op_sel_hi:[1,0,1]
	v_pk_fma_f32 v[72:73], v[72:73], v[82:83], v[56:57] op_sel_hi:[1,0,1]
	v_max_f32_e32 v77, 0, v77
	v_max_f32_e32 v76, 0, v76
	v_pk_fma_f32 v[78:79], v[78:79], v[82:83], v[66:67] op_sel_hi:[1,0,1]
	v_max_f32_e32 v73, 0, v73
	v_max_f32_e32 v72, 0, v72
	v_max_f32_e32 v75, 0, v75
	v_max_f32_e32 v74, 0, v74
	v_pk_mul_f32 v[76:77], v[76:77], v[76:77]
	v_max_f32_e32 v79, 0, v79
	v_max_f32_e32 v78, 0, v78
	v_pk_mul_f32 v[84:85], v[74:75], v[74:75]
	v_pk_mul_f32 v[74:75], v[72:73], v[72:73]
	v_cvt_pk_bf16_f32 v72, v76, v77
	v_add_co_u32_e32 v76, vcc, s4, v154
	v_pk_fma_f32 v[50:51], v[50:51], v[82:83], v[62:63] op_sel_hi:[1,0,1]
	v_pk_fma_f32 v[48:49], v[48:49], v[82:83], v[60:61] op_sel_hi:[1,0,1]
	v_pk_mul_f32 v[78:79], v[78:79], v[78:79]
	v_addc_co_u32_e32 v77, vcc, 0, v155, vcc
	v_cvt_pk_bf16_f32 v73, v78, v79
	v_pk_fma_f32 v[54:55], v[54:55], v[82:83], v[70:71] op_sel_hi:[1,0,1]
	v_pk_fma_f32 v[52:53], v[52:53], v[82:83], v[68:69] op_sel_hi:[1,0,1]
	v_max_f32_e32 v49, 0, v49
	v_max_f32_e32 v48, 0, v48
	v_max_f32_e32 v51, 0, v51
	v_max_f32_e32 v50, 0, v50
	v_cvt_pk_bf16_f32 v74, v74, v75
	v_cvt_pk_bf16_f32 v75, v84, v85
	global_store_dwordx4 v[76:77], v[72:75], off
	v_max_f32_e32 v53, 0, v53
	v_max_f32_e32 v52, 0, v52
	v_max_f32_e32 v55, 0, v55
	v_max_f32_e32 v54, 0, v54
	v_pk_mul_f32 v[72:73], v[50:51], v[50:51]
	v_pk_mul_f32 v[50:51], v[48:49], v[48:49]
	v_pk_mul_f32 v[54:55], v[54:55], v[54:55]
	v_pk_mul_f32 v[52:53], v[52:53], v[52:53]
	s_mov_b64 s[4:5], 0x120000
	v_cvt_pk_bf16_f32 v48, v52, v53
	v_cvt_pk_bf16_f32 v49, v54, v55
	v_cvt_pk_bf16_f32 v50, v50, v51
	v_cvt_pk_bf16_f32 v51, v72, v73
	global_store_dwordx4 v[80:81], v[48:51], off offset:256
	s_nop 0
	s_nop 0
	v_lshl_add_u64 v[48:49], v[154:155], 0, s[4:5]
	s_mov_b32 s4, 0x120000
	v_fmamk_f32 v50, v182, 0x3a800000, v199
	v_rsq_f32_e32 v50, v50
	s_nop 0
	v_pk_fma_f32 v[44:45], v[44:45], v[50:51], v[64:65] op_sel_hi:[1,0,1]
	v_pk_fma_f32 v[42:43], v[42:43], v[50:51], v[58:59] op_sel_hi:[1,0,1]
	v_pk_fma_f32 v[40:41], v[40:41], v[50:51], v[56:57] op_sel_hi:[1,0,1]
	v_max_f32_e32 v45, 0, v45
	v_max_f32_e32 v44, 0, v44
; __device__ __forceinline__ unsigned cvt_pk_bf16(float lo, float hi) { unsigned r; asm volatile("v_cvt_pk_bf16_f32 %0, %1, %2" : "=v"(r) : "v"(lo), "v"(hi)); return r; }
;     __device__ __forceinline__ void operator()(const f32x4 (&acc)[2][2][4][2], const Unit& u, int wr, int wc, int fr, int fq) const {
;     ...
;             for (int m = 0; m < 4; ++m) { bf16_t* rowp = base + (size_t)(row0 + ai * HALF + m * 16) * ldc + col0;
;                 const float rs = rowss ? __builtin_amdgcn_rsqf(rowss[row0 + ai * HALF + m * 16] * (1.0f / 1024.0f) + 1e-6f) : 1.0f;
; #pragma unroll
;                 for (int bj = 0; bj < 2; ++bj) { f32x4 v0 = acc[ai][bj][m][0] * rs + bv[bj][0], v1 = acc[ai][bj][m][1] * rs + bv[bj][1];
;                     if (ACT == 1) { f32x2 a = gelu_pk((f32x2){v0[0], v0[1]}), b = gelu_pk((f32x2){v0[2], v0[3]}), c = gelu_pk((f32x2){v1[0], v1[1]}), d = gelu_pk((f32x2){v1[2], v1[3]});
;                         v0 = (f32x4){a.x, a.y, b.x, b.y}; v1 = (f32x4){c.x, c.y, d.x, d.y}; }
;                     if (ACT == 2) { v0 = __builtin_elementwise_max(v0, (f32x4){0.f, 0.f, 0.f, 0.f}); v1 = __builtin_elementwise_max(v1, (f32x4){0.f, 0.f, 0.f, 0.f}); v0 = v0 * v0; v1 = v1 * v1; }
;                     v0 = v0 * sc; v1 = v1 * sc; u32x4 w; w.x = cvt_pk_bf16(v0[0], v0[1]); w.y = cvt_pk_bf16(v0[2], v0[3]); w.z = cvt_pk_bf16(v1[0], v1[1]); w.w = cvt_pk_bf16(v1[2], v1[3]);
;                     *(u32x4*)(rowp + bj * HALF) = w; } }
	v_pk_fma_f32 v[46:47], v[46:47], v[50:51], v[66:67] op_sel_hi:[1,0,1]
	v_max_f32_e32 v41, 0, v41
	v_max_f32_e32 v40, 0, v40
	v_max_f32_e32 v43, 0, v43
	v_max_f32_e32 v42, 0, v42
	v_pk_mul_f32 v[44:45], v[44:45], v[44:45]
	v_max_f32_e32 v47, 0, v47
	v_max_f32_e32 v46, 0, v46
	v_pk_mul_f32 v[52:53], v[42:43], v[42:43]
	v_pk_mul_f32 v[42:43], v[40:41], v[40:41]
	v_cvt_pk_bf16_f32 v40, v44, v45
	v_add_co_u32_e32 v44, vcc, s4, v154
	v_pk_fma_f32 v[34:35], v[34:35], v[50:51], v[62:63] op_sel_hi:[1,0,1]
	v_pk_fma_f32 v[32:33], v[32:33], v[50:51], v[60:61] op_sel_hi:[1,0,1]
	v_pk_mul_f32 v[46:47], v[46:47], v[46:47]
	v_addc_co_u32_e32 v45, vcc, 0, v155, vcc
	v_cvt_pk_bf16_f32 v41, v46, v47
	v_pk_fma_f32 v[38:39], v[38:39], v[50:51], v[70:71] op_sel_hi:[1,0,1]
	v_pk_fma_f32 v[36:37], v[36:37], v[50:51], v[68:69] op_sel_hi:[1,0,1]
	v_max_f32_e32 v33, 0, v33
	v_max_f32_e32 v32, 0, v32
	v_max_f32_e32 v35, 0, v35
	v_max_f32_e32 v34, 0, v34
	v_cvt_pk_bf16_f32 v42, v42, v43
	v_cvt_pk_bf16_f32 v43, v52, v53
	global_store_dwordx4 v[44:45], v[40:43], off
	v_max_f32_e32 v37, 0, v37
	v_max_f32_e32 v36, 0, v36
	v_max_f32_e32 v39, 0, v39
	v_max_f32_e32 v38, 0, v38
	v_pk_mul_f32 v[40:41], v[34:35], v[34:35]
	v_pk_mul_f32 v[34:35], v[32:33], v[32:33]
	v_pk_mul_f32 v[38:39], v[38:39], v[38:39]
	v_pk_mul_f32 v[36:37], v[36:37], v[36:37]
	s_mov_b64 s[4:5], 0x140000
	v_cvt_pk_bf16_f32 v32, v36, v37
	v_cvt_pk_bf16_f32 v33, v38, v39
	v_cvt_pk_bf16_f32 v34, v34, v35
	v_cvt_pk_bf16_f32 v35, v40, v41
	global_store_dwordx4 v[48:49], v[32:35], off offset:256
	s_nop 0
	s_nop 0
	v_lshl_add_u64 v[32:33], v[154:155], 0, s[4:5]
	s_mov_b32 s4, 0x140000
	v_fmamk_f32 v34, v184, 0x3a800000, v199
	v_rsq_f32_e32 v34, v34
	s_nop 0
	v_pk_fma_f32 v[28:29], v[28:29], v[34:35], v[64:65] op_sel_hi:[1,0,1]
	v_pk_fma_f32 v[26:27], v[26:27], v[34:35], v[58:59] op_sel_hi:[1,0,1]
	v_pk_fma_f32 v[24:25], v[24:25], v[34:35], v[56:57] op_sel_hi:[1,0,1]
	v_max_f32_e32 v29, 0, v29
	v_max_f32_e32 v28, 0, v28
	v_pk_fma_f32 v[30:31], v[30:31], v[34:35], v[66:67] op_sel_hi:[1,0,1]
	v_max_f32_e32 v25, 0, v25
	v_max_f32_e32 v24, 0, v24
	v_max_f32_e32 v27, 0, v27
	v_max_f32_e32 v26, 0, v26
	v_pk_mul_f32 v[28:29], v[28:29], v[28:29]
	v_max_f32_e32 v31, 0, v31
	v_max_f32_e32 v30, 0, v30
	v_pk_mul_f32 v[36:37], v[26:27], v[26:27]
	v_pk_mul_f32 v[26:27], v[24:25], v[24:25]
	v_cvt_pk_bf16_f32 v24, v28, v29
	v_add_co_u32_e32 v28, vcc, s4, v154
	v_pk_fma_f32 v[18:19], v[18:19], v[34:35], v[62:63] op_sel_hi:[1,0,1]
	v_pk_fma_f32 v[16:17], v[16:17], v[34:35], v[60:61] op_sel_hi:[1,0,1]
	v_pk_mul_f32 v[30:31], v[30:31], v[30:31]
	v_addc_co_u32_e32 v29, vcc, 0, v155, vcc
	v_cvt_pk_bf16_f32 v25, v30, v31
	v_pk_fma_f32 v[22:23], v[22:23], v[34:35], v[70:71] op_sel_hi:[1,0,1]
	v_pk_fma_f32 v[20:21], v[20:21], v[34:35], v[68:69] op_sel_hi:[1,0,1]
	v_max_f32_e32 v17, 0, v17
	v_max_f32_e32 v16, 0, v16
	v_max_f32_e32 v19, 0, v19
	v_max_f32_e32 v18, 0, v18
	v_cvt_pk_bf16_f32 v26, v26, v27
	v_cvt_pk_bf16_f32 v27, v36, v37
	global_store_dwordx4 v[28:29], v[24:27], off
	v_max_f32_e32 v21, 0, v21
	v_max_f32_e32 v20, 0, v20
	v_max_f32_e32 v23, 0, v23
	v_max_f32_e32 v22, 0, v22
	v_pk_mul_f32 v[24:25], v[18:19], v[18:19]
	v_pk_mul_f32 v[18:19], v[16:17], v[16:17]
	v_pk_mul_f32 v[22:23], v[22:23], v[22:23]
	v_pk_mul_f32 v[20:21], v[20:21], v[20:21]
	s_mov_b64 s[4:5], 0x160000
	v_cvt_pk_bf16_f32 v16, v20, v21
	v_cvt_pk_bf16_f32 v17, v22, v23
	v_cvt_pk_bf16_f32 v18, v18, v19
	v_cvt_pk_bf16_f32 v19, v24, v25
	global_store_dwordx4 v[32:33], v[16:19], off offset:256
	s_nop 0
	s_nop 0
	v_lshl_add_u64 v[18:19], v[154:155], 0, s[4:5]
	s_mov_b32 s4, 0x160000
	v_fmamk_f32 v16, v186, 0x3a800000, v199
	v_rsq_f32_e32 v16, v16
	s_nop 0
	v_pk_fma_f32 v[12:13], v[12:13], v[16:17], v[64:65] op_sel_hi:[1,0,1]
	v_pk_fma_f32 v[10:11], v[10:11], v[16:17], v[58:59] op_sel_hi:[1,0,1]
	v_pk_fma_f32 v[8:9], v[8:9], v[16:17], v[56:57] op_sel_hi:[1,0,1]
	v_max_f32_e32 v13, 0, v13
	v_max_f32_e32 v12, 0, v12
	v_pk_fma_f32 v[14:15], v[14:15], v[16:17], v[66:67] op_sel_hi:[1,0,1]
	v_max_f32_e32 v9, 0, v9
	v_max_f32_e32 v8, 0, v8
	v_max_f32_e32 v11, 0, v11
	v_max_f32_e32 v10, 0, v10
	v_pk_mul_f32 v[12:13], v[12:13], v[12:13]
	v_max_f32_e32 v15, 0, v15
	v_max_f32_e32 v14, 0, v14
	v_pk_mul_f32 v[20:21], v[10:11], v[10:11]
	v_pk_mul_f32 v[10:11], v[8:9], v[8:9]
	v_cvt_pk_bf16_f32 v8, v12, v13
	v_add_co_u32_e32 v12, vcc, s4, v154
	v_pk_fma_f32 v[2:3], v[2:3], v[16:17], v[62:63] op_sel_hi:[1,0,1]
	v_pk_fma_f32 v[0:1], v[0:1], v[16:17], v[60:61] op_sel_hi:[1,0,1]
	v_pk_mul_f32 v[14:15], v[14:15], v[14:15]
	v_addc_co_u32_e32 v13, vcc, 0, v155, vcc
	v_cvt_pk_bf16_f32 v9, v14, v15
	v_pk_fma_f32 v[6:7], v[6:7], v[16:17], v[70:71] op_sel_hi:[1,0,1]
	v_pk_fma_f32 v[4:5], v[4:5], v[16:17], v[68:69] op_sel_hi:[1,0,1]
	v_max_f32_e32 v1, 0, v1
	v_max_f32_e32 v0, 0, v0
	v_max_f32_e32 v3, 0, v3
	v_max_f32_e32 v2, 0, v2
	v_cvt_pk_bf16_f32 v10, v10, v11
	v_cvt_pk_bf16_f32 v11, v20, v21
	global_store_dwordx4 v[12:13], v[8:11], off
	v_max_f32_e32 v5, 0, v5
	v_max_f32_e32 v4, 0, v4
	v_max_f32_e32 v7, 0, v7
	v_max_f32_e32 v6, 0, v6
	v_pk_mul_f32 v[8:9], v[2:3], v[2:3]
	v_pk_mul_f32 v[2:3], v[0:1], v[0:1]
	s_mov_b64 s[4:5], -1
	s_andn2_b64 vcc, exec, s[0:1]
	v_pk_mul_f32 v[6:7], v[6:7], v[6:7]
	v_pk_mul_f32 v[4:5], v[4:5], v[4:5]
	s_nop 0
	v_cvt_pk_bf16_f32 v0, v4, v5
	v_cvt_pk_bf16_f32 v1, v6, v7
	v_cvt_pk_bf16_f32 v2, v2, v3
	v_cvt_pk_bf16_f32 v3, v8, v9
	global_store_dwordx4 v[18:19], v[0:3], off offset:256
	s_cbranch_vccnz .LBB0_1127
	s_andn2_b64 vcc, exec, s[2:3]
	s_cbranch_vccnz .LBB0_1126
	s_barrier
	s_branch .LBB0_1126
